# as v44 plus s_waitcnt vmcnt(0) at the norm loop exits (retire clamped prefetch loads before the VGPRs are reused)
# speedup vs baseline: 1.0094x; 1.0010x over previous
; __device__ __forceinline__ unsigned cvt_pk_bf16(float lo, float hi) { unsigned r; asm volatile("v_cvt_pk_bf16_f32 %0, %1, %2" : "=v"(r) : "v"(lo), "v"(hi)); return r; }
; __device__ __forceinline__ void phase_norm_mod(const float* x, const float* mod_shift, const float* mod_scale, bf16_t* H, int) {
;     ...
;         for (int r = 0; r < NR; ++r) { const int m = M - 1 - (m0 + r * NGW < M ? m0 + r * NGW : m0); const f32x4* xr = (const f32x4*)(x + (size_t)m * D) + lane;
; #pragma unroll
;             for (int j = 0; j < 4; ++j) v[r][j] = xr[64 * j]; }
; #pragma unroll
;         for (int r = 0; r < NR; ++r) { const int m = M - 1 - (m0 + r * NGW); if (m >= 0) {
;             const int b = m >> 12; float s = 0.f;
; #pragma unroll
;             for (int j = 0; j < 4; ++j) s += (v[r][j].x * v[r][j].x + v[r][j].y * v[r][j].y) + (v[r][j].z * v[r][j].z + v[r][j].w * v[r][j].w);
;             const float rstd = 1.0f / sqrtf(wave_sum(s) * (1.f / D) + 1e-6f);
;             const f32x4* sh = (const f32x4*)(mod_shift + (size_t)b * 6144) + lane;
;             const f32x4* sc = (const f32x4*)(mod_scale + (size_t)b * 6144) + lane;
;             u32x2* o = (u32x2*)(H + (size_t)m * D) + lane;
; #pragma unroll
;             for (int j = 0; j < 4; ++j) { const f32x4 a = sh[64 * j], c = sc[64 * j]; const f32x4 h = v[r][j] * rstd * (c + 1.0f) + a;
;                 u32x2 w; w.x = cvt_pk_bf16(h.x, h.y); w.y = cvt_pk_bf16(h.z, h.w); o[64 * j] = w; } } }
.LNa_loop:
	s_cmp_lt_u32 s18, 0x10000
	s_cbranch_scc0 .LNa_done
	s_waitcnt vmcnt(24)
	v_pk_mul_f32 v[172:173], v[0:1], v[0:1]
	v_pk_mul_f32 v[174:175], v[2:3], v[2:3]
	v_pk_fma_f32 v[172:173], v[4:5], v[4:5], v[172:173]
	v_pk_fma_f32 v[174:175], v[6:7], v[6:7], v[174:175]
	v_pk_fma_f32 v[172:173], v[8:9], v[8:9], v[172:173]
	v_pk_fma_f32 v[174:175], v[10:11], v[10:11], v[174:175]
	v_pk_fma_f32 v[172:173], v[12:13], v[12:13], v[172:173]
	v_pk_fma_f32 v[174:175], v[14:15], v[14:15], v[174:175]
	v_pk_add_f32 v[172:173], v[172:173], v[174:175]
	s_sub_u32 s3, 0xffff, s18
	s_lshl_b32 s4, s3, 11
	v_add_f32_e32 v160, v172, v173
	s_add_u32 s16, s88, s4
	s_addc_u32 s17, s89, 0
	s_nop 1
	v_add_f32_dpp v160, v160, v160 quad_perm:[1,0,3,2] row_mask:0xf bank_mask:0xf bound_ctrl:1
	s_nop 1
	v_add_f32_dpp v160, v160, v160 quad_perm:[2,3,0,1] row_mask:0xf bank_mask:0xf bound_ctrl:1
	s_nop 1
	v_add_f32_dpp v160, v160, v160 row_half_mirror row_mask:0xf bank_mask:0xf bound_ctrl:1
	s_nop 1
	v_add_f32_dpp v160, v160, v160 row_mirror row_mask:0xf bank_mask:0xf bound_ctrl:1
	s_add_u32 s16, s16, 0x3c00000
	s_addc_u32 s17, s17, 0
	v_readlane_b32 s4, v160, 0
	v_readlane_b32 s5, v160, 16
	v_readlane_b32 s3, v160, 32
	s_nop 1
	v_mov_b32_e32 v161, s4
	v_add_f32_e32 v161, s5, v161
	v_readlane_b32 s4, v160, 48
	v_add_f32_e32 v161, s3, v161
	s_nop 1
	v_add_f32_e32 v160, s4, v161
	v_fmamk_f32 v160, v160, 0x3a800000, v170
	v_mul_f32_e32 v161, 0x4f800000, v160
	v_cmp_gt_f32_e32 vcc, v178, v160
	s_nop 1
	v_cndmask_b32_e32 v162, v160, v161, vcc
	v_sqrt_f32_e32 v164, v162
	s_nop 0
	v_add_u32_e32 v165, -1, v164
	v_add_u32_e32 v166, 1, v164
	v_fma_f32 v167, -v165, v164, v162
	v_fma_f32 v168, -v166, v164, v162
	v_cmp_ge_f32_e64 s[4:5], 0, v167
	s_nop 1
	v_cndmask_b32_e64 v164, v164, v165, s[4:5]
	v_cmp_lt_f32_e64 s[4:5], 0, v168
	s_nop 1
	v_cndmask_b32_e64 v164, v164, v166, s[4:5]
	v_mul_f32_e32 v165, 0x37800000, v164
	v_cndmask_b32_e32 v164, v164, v165, vcc
	v_cmp_class_f32_e32 vcc, v162, v171
	s_nop 1
	v_cndmask_b32_e32 v162, v164, v162, vcc
	v_div_scale_f32 v164, s[4:5], v162, v162, 1.0
	v_rcp_f32_e32 v165, v164
	v_div_scale_f32 v166, vcc, 1.0, v162, 1.0
	v_fma_f32 v167, -v164, v165, 1.0
	v_fmac_f32_e32 v165, v167, v165
	v_mul_f32_e32 v167, v166, v165
	v_fma_f32 v168, -v164, v167, v166
	v_fmac_f32_e32 v167, v168, v165
	v_fma_f32 v164, -v164, v167, v166
	v_div_fmas_f32 v164, v164, v165, v167
	v_div_fixup_f32 v162, v164, v162, 1.0
	v_pk_mul_f32 v[0:1], v[0:1], v[162:163] op_sel_hi:[1,0]
	v_pk_mul_f32 v[2:3], v[2:3], v[162:163] op_sel_hi:[1,0]
	v_pk_add_f32 v[16:17], v[16:17], 1.0 op_sel_hi:[1,0]
	v_pk_add_f32 v[18:19], v[18:19], 1.0 op_sel_hi:[1,0]
	v_pk_fma_f32 v[0:1], v[16:17], v[0:1], v[32:33]
	v_pk_fma_f32 v[2:3], v[18:19], v[2:3], v[34:35]
	v_cvt_pk_bf16_f32 v152, v0, v1
	v_cvt_pk_bf16_f32 v153, v2, v3
	v_pk_mul_f32 v[4:5], v[4:5], v[162:163] op_sel_hi:[1,0]
	v_pk_mul_f32 v[6:7], v[6:7], v[162:163] op_sel_hi:[1,0]
	v_pk_add_f32 v[20:21], v[20:21], 1.0 op_sel_hi:[1,0]
	v_pk_add_f32 v[22:23], v[22:23], 1.0 op_sel_hi:[1,0]
	v_pk_fma_f32 v[4:5], v[20:21], v[4:5], v[36:37]
	v_pk_fma_f32 v[6:7], v[22:23], v[6:7], v[38:39]
	v_cvt_pk_bf16_f32 v154, v4, v5
	v_cvt_pk_bf16_f32 v155, v6, v7
	v_pk_mul_f32 v[8:9], v[8:9], v[162:163] op_sel_hi:[1,0]
	v_pk_mul_f32 v[10:11], v[10:11], v[162:163] op_sel_hi:[1,0]
	v_pk_add_f32 v[24:25], v[24:25], 1.0 op_sel_hi:[1,0]
	v_pk_add_f32 v[26:27], v[26:27], 1.0 op_sel_hi:[1,0]
	v_pk_fma_f32 v[8:9], v[24:25], v[8:9], v[40:41]
	v_pk_fma_f32 v[10:11], v[26:27], v[10:11], v[42:43]
	v_cvt_pk_bf16_f32 v156, v8, v9
	v_cvt_pk_bf16_f32 v157, v10, v11
	v_pk_mul_f32 v[12:13], v[12:13], v[162:163] op_sel_hi:[1,0]
	v_pk_mul_f32 v[14:15], v[14:15], v[162:163] op_sel_hi:[1,0]
	v_pk_add_f32 v[28:29], v[28:29], 1.0 op_sel_hi:[1,0]
	v_pk_add_f32 v[30:31], v[30:31], 1.0 op_sel_hi:[1,0]
	v_pk_fma_f32 v[12:13], v[28:29], v[12:13], v[44:45]
	v_pk_fma_f32 v[14:15], v[30:31], v[14:15], v[46:47]
	v_cvt_pk_bf16_f32 v158, v12, v13
	v_cvt_pk_bf16_f32 v159, v14, v15
	global_store_dwordx2 v177, v[152:153], s[16:17]
	global_store_dwordx2 v177, v[154:155], s[16:17] offset:512
	global_store_dwordx2 v177, v[156:157], s[16:17] offset:1024
	global_store_dwordx2 v177, v[158:159], s[16:17] offset:1536
	s_add_i32 s18, s18, s1
	s_cmp_lt_u32 s18, 0x10000
	s_cselect_b32 s3, s18, s0
	s_sub_u32 s3, 0xffff, s3
	s_lshl_b32 s4, s3, 12
	s_add_u32 s6, s86, s4
	s_addc_u32 s7, s87, 0
	s_lshr_b32 s4, s3, 12
	s_mul_i32 s4, s4, 0x6000
	s_add_u32 s12, s88, s4
	s_addc_u32 s13, s89, 0
	s_add_u32 s14, s12, 0x104000
	s_addc_u32 s15, s13, 0
	s_add_u32 s12, s12, 0x103000
	s_addc_u32 s13, s13, 0
	global_load_dwordx4 v[0:3], v176, s[6:7]
	global_load_dwordx4 v[4:7], v176, s[6:7] offset:1024
	global_load_dwordx4 v[8:11], v176, s[6:7] offset:2048
	global_load_dwordx4 v[12:15], v176, s[6:7] offset:3072
	global_load_dwordx4 v[16:19], v176, s[14:15]
	global_load_dwordx4 v[20:23], v176, s[14:15] offset:1024
	global_load_dwordx4 v[24:27], v176, s[14:15] offset:2048
	global_load_dwordx4 v[28:31], v176, s[14:15] offset:3072
	global_load_dwordx4 v[32:35], v176, s[12:13]
	global_load_dwordx4 v[36:39], v176, s[12:13] offset:1024
	global_load_dwordx4 v[40:43], v176, s[12:13] offset:2048
	global_load_dwordx4 v[44:47], v176, s[12:13] offset:3072
	s_cmp_lt_u32 s19, 0x10000
	s_cbranch_scc0 .LNa_done
; __device__ __forceinline__ unsigned cvt_pk_bf16(float lo, float hi) { unsigned r; asm volatile("v_cvt_pk_bf16_f32 %0, %1, %2" : "=v"(r) : "v"(lo), "v"(hi)); return r; }
; __device__ __forceinline__ void phase_norm_mod(const float* x, const float* mod_shift, const float* mod_scale, bf16_t* H, int) {
;     ...
;         for (int r = 0; r < NR; ++r) { const int m = M - 1 - (m0 + r * NGW < M ? m0 + r * NGW : m0); const f32x4* xr = (const f32x4*)(x + (size_t)m * D) + lane;
; #pragma unroll
;             for (int j = 0; j < 4; ++j) v[r][j] = xr[64 * j]; }
; #pragma unroll
;         for (int r = 0; r < NR; ++r) { const int m = M - 1 - (m0 + r * NGW); if (m >= 0) {
;             const int b = m >> 12; float s = 0.f;
; #pragma unroll
;             for (int j = 0; j < 4; ++j) s += (v[r][j].x * v[r][j].x + v[r][j].y * v[r][j].y) + (v[r][j].z * v[r][j].z + v[r][j].w * v[r][j].w);
;             const float rstd = 1.0f / sqrtf(wave_sum(s) * (1.f / D) + 1e-6f);
;             const f32x4* sh = (const f32x4*)(mod_shift + (size_t)b * 6144) + lane;
;             const f32x4* sc = (const f32x4*)(mod_scale + (size_t)b * 6144) + lane;
;             u32x2* o = (u32x2*)(H + (size_t)m * D) + lane;
; #pragma unroll
;             for (int j = 0; j < 4; ++j) { const f32x4 a = sh[64 * j], c = sc[64 * j]; const f32x4 h = v[r][j] * rstd * (c + 1.0f) + a;
;                 u32x2 w; w.x = cvt_pk_bf16(h.x, h.y); w.y = cvt_pk_bf16(h.z, h.w); o[64 * j] = w; } } }
	s_waitcnt vmcnt(24)
	v_pk_mul_f32 v[172:173], v[48:49], v[48:49]
	v_pk_mul_f32 v[174:175], v[50:51], v[50:51]
	v_pk_fma_f32 v[172:173], v[52:53], v[52:53], v[172:173]
	v_pk_fma_f32 v[174:175], v[54:55], v[54:55], v[174:175]
	v_pk_fma_f32 v[172:173], v[56:57], v[56:57], v[172:173]
	v_pk_fma_f32 v[174:175], v[58:59], v[58:59], v[174:175]
	v_pk_fma_f32 v[172:173], v[60:61], v[60:61], v[172:173]
	v_pk_fma_f32 v[174:175], v[62:63], v[62:63], v[174:175]
	v_pk_add_f32 v[172:173], v[172:173], v[174:175]
	s_sub_u32 s3, 0xffff, s19
	s_lshl_b32 s4, s3, 11
	v_add_f32_e32 v160, v172, v173
	s_add_u32 s16, s88, s4
	s_addc_u32 s17, s89, 0
	s_nop 1
	v_add_f32_dpp v160, v160, v160 quad_perm:[1,0,3,2] row_mask:0xf bank_mask:0xf bound_ctrl:1
	s_nop 1
	v_add_f32_dpp v160, v160, v160 quad_perm:[2,3,0,1] row_mask:0xf bank_mask:0xf bound_ctrl:1
	s_nop 1
	v_add_f32_dpp v160, v160, v160 row_half_mirror row_mask:0xf bank_mask:0xf bound_ctrl:1
	s_nop 1
	v_add_f32_dpp v160, v160, v160 row_mirror row_mask:0xf bank_mask:0xf bound_ctrl:1
	s_add_u32 s16, s16, 0x3c00000
	s_addc_u32 s17, s17, 0
	v_readlane_b32 s4, v160, 0
	v_readlane_b32 s5, v160, 16
	v_readlane_b32 s3, v160, 32
	s_nop 1
	v_mov_b32_e32 v161, s4
	v_add_f32_e32 v161, s5, v161
	v_readlane_b32 s4, v160, 48
	v_add_f32_e32 v161, s3, v161
	s_nop 1
	v_add_f32_e32 v160, s4, v161
	v_fmamk_f32 v160, v160, 0x3a800000, v170
	v_mul_f32_e32 v161, 0x4f800000, v160
	v_cmp_gt_f32_e32 vcc, v178, v160
	s_nop 1
	v_cndmask_b32_e32 v162, v160, v161, vcc
	v_sqrt_f32_e32 v164, v162
	s_nop 0
	v_add_u32_e32 v165, -1, v164
	v_add_u32_e32 v166, 1, v164
	v_fma_f32 v167, -v165, v164, v162
	v_fma_f32 v168, -v166, v164, v162
	v_cmp_ge_f32_e64 s[4:5], 0, v167
	s_nop 1
	v_cndmask_b32_e64 v164, v164, v165, s[4:5]
	v_cmp_lt_f32_e64 s[4:5], 0, v168
	s_nop 1
	v_cndmask_b32_e64 v164, v164, v166, s[4:5]
	v_mul_f32_e32 v165, 0x37800000, v164
	v_cndmask_b32_e32 v164, v164, v165, vcc
	v_cmp_class_f32_e32 vcc, v162, v171
	s_nop 1
	v_cndmask_b32_e32 v162, v164, v162, vcc
	v_div_scale_f32 v164, s[4:5], v162, v162, 1.0
	v_rcp_f32_e32 v165, v164
	v_div_scale_f32 v166, vcc, 1.0, v162, 1.0
	v_fma_f32 v167, -v164, v165, 1.0
	v_fmac_f32_e32 v165, v167, v165
	v_mul_f32_e32 v167, v166, v165
	v_fma_f32 v168, -v164, v167, v166
	v_fmac_f32_e32 v167, v168, v165
	v_fma_f32 v164, -v164, v167, v166
	v_div_fmas_f32 v164, v164, v165, v167
	v_div_fixup_f32 v162, v164, v162, 1.0
	v_pk_mul_f32 v[48:49], v[48:49], v[162:163] op_sel_hi:[1,0]
	v_pk_mul_f32 v[50:51], v[50:51], v[162:163] op_sel_hi:[1,0]
	v_pk_add_f32 v[64:65], v[64:65], 1.0 op_sel_hi:[1,0]
	v_pk_add_f32 v[66:67], v[66:67], 1.0 op_sel_hi:[1,0]
	v_pk_fma_f32 v[48:49], v[64:65], v[48:49], v[80:81]
	v_pk_fma_f32 v[50:51], v[66:67], v[50:51], v[82:83]
	v_cvt_pk_bf16_f32 v152, v48, v49
	v_cvt_pk_bf16_f32 v153, v50, v51
	v_pk_mul_f32 v[52:53], v[52:53], v[162:163] op_sel_hi:[1,0]
	v_pk_mul_f32 v[54:55], v[54:55], v[162:163] op_sel_hi:[1,0]
	v_pk_add_f32 v[68:69], v[68:69], 1.0 op_sel_hi:[1,0]
	v_pk_add_f32 v[70:71], v[70:71], 1.0 op_sel_hi:[1,0]
	v_pk_fma_f32 v[52:53], v[68:69], v[52:53], v[84:85]
	v_pk_fma_f32 v[54:55], v[70:71], v[54:55], v[86:87]
	v_cvt_pk_bf16_f32 v154, v52, v53
	v_cvt_pk_bf16_f32 v155, v54, v55
	v_pk_mul_f32 v[56:57], v[56:57], v[162:163] op_sel_hi:[1,0]
	v_pk_mul_f32 v[58:59], v[58:59], v[162:163] op_sel_hi:[1,0]
	v_pk_add_f32 v[72:73], v[72:73], 1.0 op_sel_hi:[1,0]
	v_pk_add_f32 v[74:75], v[74:75], 1.0 op_sel_hi:[1,0]
	v_pk_fma_f32 v[56:57], v[72:73], v[56:57], v[88:89]
	v_pk_fma_f32 v[58:59], v[74:75], v[58:59], v[90:91]
	v_cvt_pk_bf16_f32 v156, v56, v57
	v_cvt_pk_bf16_f32 v157, v58, v59
	v_pk_mul_f32 v[60:61], v[60:61], v[162:163] op_sel_hi:[1,0]
	v_pk_mul_f32 v[62:63], v[62:63], v[162:163] op_sel_hi:[1,0]
	v_pk_add_f32 v[76:77], v[76:77], 1.0 op_sel_hi:[1,0]
	v_pk_add_f32 v[78:79], v[78:79], 1.0 op_sel_hi:[1,0]
	v_pk_fma_f32 v[60:61], v[76:77], v[60:61], v[92:93]
	v_pk_fma_f32 v[62:63], v[78:79], v[62:63], v[94:95]
	v_cvt_pk_bf16_f32 v158, v60, v61
	v_cvt_pk_bf16_f32 v159, v62, v63
	global_store_dwordx2 v177, v[152:153], s[16:17]
	global_store_dwordx2 v177, v[154:155], s[16:17] offset:512
	global_store_dwordx2 v177, v[156:157], s[16:17] offset:1024
	global_store_dwordx2 v177, v[158:159], s[16:17] offset:1536
	s_add_i32 s19, s19, s1
	s_cmp_lt_u32 s19, 0x10000
	s_cselect_b32 s3, s19, s0
	s_sub_u32 s3, 0xffff, s3
	s_lshl_b32 s4, s3, 12
	s_add_u32 s6, s86, s4
	s_addc_u32 s7, s87, 0
	s_lshr_b32 s4, s3, 12
	s_mul_i32 s4, s4, 0x6000
	s_add_u32 s12, s88, s4
	s_addc_u32 s13, s89, 0
	s_add_u32 s14, s12, 0x104000
	s_addc_u32 s15, s13, 0
	s_add_u32 s12, s12, 0x103000
	s_addc_u32 s13, s13, 0
	global_load_dwordx4 v[48:51], v176, s[6:7]
	global_load_dwordx4 v[52:55], v176, s[6:7] offset:1024
	global_load_dwordx4 v[56:59], v176, s[6:7] offset:2048
	global_load_dwordx4 v[60:63], v176, s[6:7] offset:3072
	global_load_dwordx4 v[64:67], v176, s[14:15]
	global_load_dwordx4 v[68:71], v176, s[14:15] offset:1024
	global_load_dwordx4 v[72:75], v176, s[14:15] offset:2048
	global_load_dwordx4 v[76:79], v176, s[14:15] offset:3072
	global_load_dwordx4 v[80:83], v176, s[12:13]
	global_load_dwordx4 v[84:87], v176, s[12:13] offset:1024
	global_load_dwordx4 v[88:91], v176, s[12:13] offset:2048
	global_load_dwordx4 v[92:95], v176, s[12:13] offset:3072
	s_cmp_lt_u32 s20, 0x10000
	s_cbranch_scc0 .LNa_done
; __device__ __forceinline__ unsigned cvt_pk_bf16(float lo, float hi) { unsigned r; asm volatile("v_cvt_pk_bf16_f32 %0, %1, %2" : "=v"(r) : "v"(lo), "v"(hi)); return r; }
; __device__ __forceinline__ void phase_norm_mod(const float* x, const float* mod_shift, const float* mod_scale, bf16_t* H, int) {
;     ...
;         for (int r = 0; r < NR; ++r) { const int m = M - 1 - (m0 + r * NGW < M ? m0 + r * NGW : m0); const f32x4* xr = (const f32x4*)(x + (size_t)m * D) + lane;
; #pragma unroll
;             for (int j = 0; j < 4; ++j) v[r][j] = xr[64 * j]; }
; #pragma unroll
;         for (int r = 0; r < NR; ++r) { const int m = M - 1 - (m0 + r * NGW); if (m >= 0) {
;             const int b = m >> 12; float s = 0.f;
; #pragma unroll
;             for (int j = 0; j < 4; ++j) s += (v[r][j].x * v[r][j].x + v[r][j].y * v[r][j].y) + (v[r][j].z * v[r][j].z + v[r][j].w * v[r][j].w);
;             const float rstd = 1.0f / sqrtf(wave_sum(s) * (1.f / D) + 1e-6f);
;             const f32x4* sh = (const f32x4*)(mod_shift + (size_t)b * 6144) + lane;
;             const f32x4* sc = (const f32x4*)(mod_scale + (size_t)b * 6144) + lane;
;             u32x2* o = (u32x2*)(H + (size_t)m * D) + lane;
; #pragma unroll
;             for (int j = 0; j < 4; ++j) { const f32x4 a = sh[64 * j], c = sc[64 * j]; const f32x4 h = v[r][j] * rstd * (c + 1.0f) + a;
;                 u32x2 w; w.x = cvt_pk_bf16(h.x, h.y); w.y = cvt_pk_bf16(h.z, h.w); o[64 * j] = w; } } }
	s_waitcnt vmcnt(24)
	v_pk_mul_f32 v[172:173], v[96:97], v[96:97]
	v_pk_mul_f32 v[174:175], v[98:99], v[98:99]
	v_pk_fma_f32 v[172:173], v[100:101], v[100:101], v[172:173]
	v_pk_fma_f32 v[174:175], v[102:103], v[102:103], v[174:175]
	v_pk_fma_f32 v[172:173], v[104:105], v[104:105], v[172:173]
	v_pk_fma_f32 v[174:175], v[106:107], v[106:107], v[174:175]
	v_pk_fma_f32 v[172:173], v[108:109], v[108:109], v[172:173]
	v_pk_fma_f32 v[174:175], v[110:111], v[110:111], v[174:175]
	v_pk_add_f32 v[172:173], v[172:173], v[174:175]
	s_sub_u32 s3, 0xffff, s20
	s_lshl_b32 s4, s3, 11
	v_add_f32_e32 v160, v172, v173
	s_add_u32 s16, s88, s4
	s_addc_u32 s17, s89, 0
	s_nop 1
	v_add_f32_dpp v160, v160, v160 quad_perm:[1,0,3,2] row_mask:0xf bank_mask:0xf bound_ctrl:1
	s_nop 1
	v_add_f32_dpp v160, v160, v160 quad_perm:[2,3,0,1] row_mask:0xf bank_mask:0xf bound_ctrl:1
	s_nop 1
	v_add_f32_dpp v160, v160, v160 row_half_mirror row_mask:0xf bank_mask:0xf bound_ctrl:1
	s_nop 1
	v_add_f32_dpp v160, v160, v160 row_mirror row_mask:0xf bank_mask:0xf bound_ctrl:1
	s_add_u32 s16, s16, 0x3c00000
	s_addc_u32 s17, s17, 0
	v_readlane_b32 s4, v160, 0
	v_readlane_b32 s5, v160, 16
	v_readlane_b32 s3, v160, 32
	s_nop 1
	v_mov_b32_e32 v161, s4
	v_add_f32_e32 v161, s5, v161
	v_readlane_b32 s4, v160, 48
	v_add_f32_e32 v161, s3, v161
	s_nop 1
	v_add_f32_e32 v160, s4, v161
	v_fmamk_f32 v160, v160, 0x3a800000, v170
	v_mul_f32_e32 v161, 0x4f800000, v160
	v_cmp_gt_f32_e32 vcc, v178, v160
	s_nop 1
	v_cndmask_b32_e32 v162, v160, v161, vcc
	v_sqrt_f32_e32 v164, v162
	s_nop 0
	v_add_u32_e32 v165, -1, v164
	v_add_u32_e32 v166, 1, v164
	v_fma_f32 v167, -v165, v164, v162
	v_fma_f32 v168, -v166, v164, v162
	v_cmp_ge_f32_e64 s[4:5], 0, v167
	s_nop 1
	v_cndmask_b32_e64 v164, v164, v165, s[4:5]
	v_cmp_lt_f32_e64 s[4:5], 0, v168
	s_nop 1
	v_cndmask_b32_e64 v164, v164, v166, s[4:5]
	v_mul_f32_e32 v165, 0x37800000, v164
	v_cndmask_b32_e32 v164, v164, v165, vcc
	v_cmp_class_f32_e32 vcc, v162, v171
	s_nop 1
	v_cndmask_b32_e32 v162, v164, v162, vcc
	v_div_scale_f32 v164, s[4:5], v162, v162, 1.0
	v_rcp_f32_e32 v165, v164
	v_div_scale_f32 v166, vcc, 1.0, v162, 1.0
	v_fma_f32 v167, -v164, v165, 1.0
	v_fmac_f32_e32 v165, v167, v165
	v_mul_f32_e32 v167, v166, v165
	v_fma_f32 v168, -v164, v167, v166
	v_fmac_f32_e32 v167, v168, v165
	v_fma_f32 v164, -v164, v167, v166
	v_div_fmas_f32 v164, v164, v165, v167
	v_div_fixup_f32 v162, v164, v162, 1.0
	v_pk_mul_f32 v[96:97], v[96:97], v[162:163] op_sel_hi:[1,0]
	v_pk_mul_f32 v[98:99], v[98:99], v[162:163] op_sel_hi:[1,0]
	v_pk_add_f32 v[112:113], v[112:113], 1.0 op_sel_hi:[1,0]
	v_pk_add_f32 v[114:115], v[114:115], 1.0 op_sel_hi:[1,0]
	v_pk_fma_f32 v[96:97], v[112:113], v[96:97], v[128:129]
	v_pk_fma_f32 v[98:99], v[114:115], v[98:99], v[130:131]
	v_cvt_pk_bf16_f32 v152, v96, v97
	v_cvt_pk_bf16_f32 v153, v98, v99
	v_pk_mul_f32 v[100:101], v[100:101], v[162:163] op_sel_hi:[1,0]
	v_pk_mul_f32 v[102:103], v[102:103], v[162:163] op_sel_hi:[1,0]
	v_pk_add_f32 v[116:117], v[116:117], 1.0 op_sel_hi:[1,0]
	v_pk_add_f32 v[118:119], v[118:119], 1.0 op_sel_hi:[1,0]
	v_pk_fma_f32 v[100:101], v[116:117], v[100:101], v[132:133]
	v_pk_fma_f32 v[102:103], v[118:119], v[102:103], v[134:135]
	v_cvt_pk_bf16_f32 v154, v100, v101
	v_cvt_pk_bf16_f32 v155, v102, v103
	v_pk_mul_f32 v[104:105], v[104:105], v[162:163] op_sel_hi:[1,0]
	v_pk_mul_f32 v[106:107], v[106:107], v[162:163] op_sel_hi:[1,0]
	v_pk_add_f32 v[120:121], v[120:121], 1.0 op_sel_hi:[1,0]
	v_pk_add_f32 v[122:123], v[122:123], 1.0 op_sel_hi:[1,0]
	v_pk_fma_f32 v[104:105], v[120:121], v[104:105], v[136:137]
	v_pk_fma_f32 v[106:107], v[122:123], v[106:107], v[138:139]
	v_cvt_pk_bf16_f32 v156, v104, v105
	v_cvt_pk_bf16_f32 v157, v106, v107
	v_pk_mul_f32 v[108:109], v[108:109], v[162:163] op_sel_hi:[1,0]
	v_pk_mul_f32 v[110:111], v[110:111], v[162:163] op_sel_hi:[1,0]
	v_pk_add_f32 v[124:125], v[124:125], 1.0 op_sel_hi:[1,0]
	v_pk_add_f32 v[126:127], v[126:127], 1.0 op_sel_hi:[1,0]
	v_pk_fma_f32 v[108:109], v[124:125], v[108:109], v[140:141]
	v_pk_fma_f32 v[110:111], v[126:127], v[110:111], v[142:143]
	v_cvt_pk_bf16_f32 v158, v108, v109
	v_cvt_pk_bf16_f32 v159, v110, v111
	global_store_dwordx2 v177, v[152:153], s[16:17]
	global_store_dwordx2 v177, v[154:155], s[16:17] offset:512
	global_store_dwordx2 v177, v[156:157], s[16:17] offset:1024
	global_store_dwordx2 v177, v[158:159], s[16:17] offset:1536
	s_add_i32 s20, s20, s1
	s_cmp_lt_u32 s20, 0x10000
	s_cselect_b32 s3, s20, s0
	s_sub_u32 s3, 0xffff, s3
	s_lshl_b32 s4, s3, 12
	s_add_u32 s6, s86, s4
	s_addc_u32 s7, s87, 0
	s_lshr_b32 s4, s3, 12
	s_mul_i32 s4, s4, 0x6000
	s_add_u32 s12, s88, s4
	s_addc_u32 s13, s89, 0
	s_add_u32 s14, s12, 0x104000
	s_addc_u32 s15, s13, 0
	s_add_u32 s12, s12, 0x103000
	s_addc_u32 s13, s13, 0
	global_load_dwordx4 v[96:99], v176, s[6:7]
	global_load_dwordx4 v[100:103], v176, s[6:7] offset:1024
	global_load_dwordx4 v[104:107], v176, s[6:7] offset:2048
	global_load_dwordx4 v[108:111], v176, s[6:7] offset:3072
	global_load_dwordx4 v[112:115], v176, s[14:15]
	global_load_dwordx4 v[116:119], v176, s[14:15] offset:1024
	global_load_dwordx4 v[120:123], v176, s[14:15] offset:2048
	global_load_dwordx4 v[124:127], v176, s[14:15] offset:3072
	global_load_dwordx4 v[128:131], v176, s[12:13]
	global_load_dwordx4 v[132:135], v176, s[12:13] offset:1024
	global_load_dwordx4 v[136:139], v176, s[12:13] offset:2048
	global_load_dwordx4 v[140:143], v176, s[12:13] offset:3072
	s_branch .LNa_loop
.LNa_done:
	s_waitcnt vmcnt(0)
.LBB0_1062:
	s_or_b64 exec, exec, s[10:11]

; __device__ __forceinline__ unsigned cvt_pk_bf16(float lo, float hi) { unsigned r; asm volatile("v_cvt_pk_bf16_f32 %0, %1, %2" : "=v"(r) : "v"(lo), "v"(hi)); return r; }
; __device__ __forceinline__ void phase_norm_mod(const float* x, const float* mod_shift, const float* mod_scale, bf16_t* H, int) {
;     ...
;         for (int r = 0; r < NR; ++r) { const int m = M - 1 - (m0 + r * NGW < M ? m0 + r * NGW : m0); const f32x4* xr = (const f32x4*)(x + (size_t)m * D) + lane;
; #pragma unroll
;             for (int j = 0; j < 4; ++j) v[r][j] = xr[64 * j]; }
; #pragma unroll
;         for (int r = 0; r < NR; ++r) { const int m = M - 1 - (m0 + r * NGW); if (m >= 0) {
;             const int b = m >> 12; float s = 0.f;
; #pragma unroll
;             for (int j = 0; j < 4; ++j) s += (v[r][j].x * v[r][j].x + v[r][j].y * v[r][j].y) + (v[r][j].z * v[r][j].z + v[r][j].w * v[r][j].w);
;             const float rstd = 1.0f / sqrtf(wave_sum(s) * (1.f / D) + 1e-6f);
;             const f32x4* sh = (const f32x4*)(mod_shift + (size_t)b * 6144) + lane;
;             const f32x4* sc = (const f32x4*)(mod_scale + (size_t)b * 6144) + lane;
;             u32x2* o = (u32x2*)(H + (size_t)m * D) + lane;
; #pragma unroll
;             for (int j = 0; j < 4; ++j) { const f32x4 a = sh[64 * j], c = sc[64 * j]; const f32x4 h = v[r][j] * rstd * (c + 1.0f) + a;
;                 u32x2 w; w.x = cvt_pk_bf16(h.x, h.y); w.y = cvt_pk_bf16(h.z, h.w); o[64 * j] = w; } } }
.LNb_loop:
	s_cmp_lt_u32 s18, 0x10000
	s_cbranch_scc0 .LNb_done
	s_waitcnt vmcnt(24)
	v_pk_mul_f32 v[172:173], v[0:1], v[0:1]
	v_pk_mul_f32 v[174:175], v[2:3], v[2:3]
	v_pk_fma_f32 v[172:173], v[4:5], v[4:5], v[172:173]
	v_pk_fma_f32 v[174:175], v[6:7], v[6:7], v[174:175]
	v_pk_fma_f32 v[172:173], v[8:9], v[8:9], v[172:173]
	v_pk_fma_f32 v[174:175], v[10:11], v[10:11], v[174:175]
	v_pk_fma_f32 v[172:173], v[12:13], v[12:13], v[172:173]
	v_pk_fma_f32 v[174:175], v[14:15], v[14:15], v[174:175]
	v_pk_add_f32 v[172:173], v[172:173], v[174:175]
	s_sub_u32 s3, 0xffff, s18
	s_lshl_b32 s4, s3, 11
	v_add_f32_e32 v160, v172, v173
	s_add_u32 s16, s88, s4
	s_addc_u32 s17, s89, 0
	s_nop 1
	v_add_f32_dpp v160, v160, v160 quad_perm:[1,0,3,2] row_mask:0xf bank_mask:0xf bound_ctrl:1
	s_nop 1
	v_add_f32_dpp v160, v160, v160 quad_perm:[2,3,0,1] row_mask:0xf bank_mask:0xf bound_ctrl:1
	s_nop 1
	v_add_f32_dpp v160, v160, v160 row_half_mirror row_mask:0xf bank_mask:0xf bound_ctrl:1
	s_nop 1
	v_add_f32_dpp v160, v160, v160 row_mirror row_mask:0xf bank_mask:0xf bound_ctrl:1
	s_add_u32 s16, s16, 0x3c00000
	s_addc_u32 s17, s17, 0
	v_readlane_b32 s4, v160, 0
	v_readlane_b32 s5, v160, 16
	v_readlane_b32 s3, v160, 32
	s_nop 1
	v_mov_b32_e32 v161, s4
	v_add_f32_e32 v161, s5, v161
	v_readlane_b32 s4, v160, 48
	v_add_f32_e32 v161, s3, v161
	s_nop 1
	v_add_f32_e32 v160, s4, v161
	v_fmamk_f32 v160, v160, 0x3a800000, v170
	v_mul_f32_e32 v161, 0x4f800000, v160
	v_cmp_gt_f32_e32 vcc, v178, v160
	s_nop 1
	v_cndmask_b32_e32 v162, v160, v161, vcc
	v_sqrt_f32_e32 v164, v162
	s_nop 0
	v_add_u32_e32 v165, -1, v164
	v_add_u32_e32 v166, 1, v164
	v_fma_f32 v167, -v165, v164, v162
	v_fma_f32 v168, -v166, v164, v162
	v_cmp_ge_f32_e64 s[4:5], 0, v167
	s_nop 1
	v_cndmask_b32_e64 v164, v164, v165, s[4:5]
	v_cmp_lt_f32_e64 s[4:5], 0, v168
	s_nop 1
	v_cndmask_b32_e64 v164, v164, v166, s[4:5]
	v_mul_f32_e32 v165, 0x37800000, v164
	v_cndmask_b32_e32 v164, v164, v165, vcc
	v_cmp_class_f32_e32 vcc, v162, v171
	s_nop 1
	v_cndmask_b32_e32 v162, v164, v162, vcc
	v_div_scale_f32 v164, s[4:5], v162, v162, 1.0
	v_rcp_f32_e32 v165, v164
	v_div_scale_f32 v166, vcc, 1.0, v162, 1.0
	v_fma_f32 v167, -v164, v165, 1.0
	v_fmac_f32_e32 v165, v167, v165
	v_mul_f32_e32 v167, v166, v165
	v_fma_f32 v168, -v164, v167, v166
	v_fmac_f32_e32 v167, v168, v165
	v_fma_f32 v164, -v164, v167, v166
	v_div_fmas_f32 v164, v164, v165, v167
	v_div_fixup_f32 v162, v164, v162, 1.0
	v_pk_mul_f32 v[0:1], v[0:1], v[162:163] op_sel_hi:[1,0]
	v_pk_mul_f32 v[2:3], v[2:3], v[162:163] op_sel_hi:[1,0]
	v_pk_add_f32 v[16:17], v[16:17], 1.0 op_sel_hi:[1,0]
	v_pk_add_f32 v[18:19], v[18:19], 1.0 op_sel_hi:[1,0]
	v_pk_fma_f32 v[0:1], v[16:17], v[0:1], v[32:33]
	v_pk_fma_f32 v[2:3], v[18:19], v[2:3], v[34:35]
	v_cvt_pk_bf16_f32 v152, v0, v1
	v_cvt_pk_bf16_f32 v153, v2, v3
	v_pk_mul_f32 v[4:5], v[4:5], v[162:163] op_sel_hi:[1,0]
	v_pk_mul_f32 v[6:7], v[6:7], v[162:163] op_sel_hi:[1,0]
	v_pk_add_f32 v[20:21], v[20:21], 1.0 op_sel_hi:[1,0]
	v_pk_add_f32 v[22:23], v[22:23], 1.0 op_sel_hi:[1,0]
	v_pk_fma_f32 v[4:5], v[20:21], v[4:5], v[36:37]
	v_pk_fma_f32 v[6:7], v[22:23], v[6:7], v[38:39]
	v_cvt_pk_bf16_f32 v154, v4, v5
	v_cvt_pk_bf16_f32 v155, v6, v7
	v_pk_mul_f32 v[8:9], v[8:9], v[162:163] op_sel_hi:[1,0]
	v_pk_mul_f32 v[10:11], v[10:11], v[162:163] op_sel_hi:[1,0]
	v_pk_add_f32 v[24:25], v[24:25], 1.0 op_sel_hi:[1,0]
	v_pk_add_f32 v[26:27], v[26:27], 1.0 op_sel_hi:[1,0]
	v_pk_fma_f32 v[8:9], v[24:25], v[8:9], v[40:41]
	v_pk_fma_f32 v[10:11], v[26:27], v[10:11], v[42:43]
	v_cvt_pk_bf16_f32 v156, v8, v9
	v_cvt_pk_bf16_f32 v157, v10, v11
	v_pk_mul_f32 v[12:13], v[12:13], v[162:163] op_sel_hi:[1,0]
	v_pk_mul_f32 v[14:15], v[14:15], v[162:163] op_sel_hi:[1,0]
	v_pk_add_f32 v[28:29], v[28:29], 1.0 op_sel_hi:[1,0]
	v_pk_add_f32 v[30:31], v[30:31], 1.0 op_sel_hi:[1,0]
	v_pk_fma_f32 v[12:13], v[28:29], v[12:13], v[44:45]
	v_pk_fma_f32 v[14:15], v[30:31], v[14:15], v[46:47]
	v_cvt_pk_bf16_f32 v158, v12, v13
	v_cvt_pk_bf16_f32 v159, v14, v15
	global_store_dwordx2 v177, v[152:153], s[16:17]
	global_store_dwordx2 v177, v[154:155], s[16:17] offset:512
	global_store_dwordx2 v177, v[156:157], s[16:17] offset:1024
	global_store_dwordx2 v177, v[158:159], s[16:17] offset:1536
	s_add_i32 s18, s18, s1
	s_cmp_lt_u32 s18, 0x10000
	s_cselect_b32 s3, s18, s0
	s_sub_u32 s3, 0xffff, s3
	s_lshl_b32 s4, s3, 12
	s_add_u32 s6, s86, s4
	s_addc_u32 s7, s87, 0
	s_lshr_b32 s4, s3, 12
	s_mul_i32 s4, s4, 0x6000
	s_add_u32 s12, s88, s4
	s_addc_u32 s13, s89, 0
	s_add_u32 s14, s12, 0x164000
	s_addc_u32 s15, s13, 0
	s_add_u32 s12, s12, 0x163000
	s_addc_u32 s13, s13, 0
	global_load_dwordx4 v[0:3], v176, s[6:7]
	global_load_dwordx4 v[4:7], v176, s[6:7] offset:1024
	global_load_dwordx4 v[8:11], v176, s[6:7] offset:2048
	global_load_dwordx4 v[12:15], v176, s[6:7] offset:3072
	global_load_dwordx4 v[16:19], v176, s[14:15]
	global_load_dwordx4 v[20:23], v176, s[14:15] offset:1024
	global_load_dwordx4 v[24:27], v176, s[14:15] offset:2048
	global_load_dwordx4 v[28:31], v176, s[14:15] offset:3072
	global_load_dwordx4 v[32:35], v176, s[12:13]
	global_load_dwordx4 v[36:39], v176, s[12:13] offset:1024
	global_load_dwordx4 v[40:43], v176, s[12:13] offset:2048
	global_load_dwordx4 v[44:47], v176, s[12:13] offset:3072
	s_cmp_lt_u32 s19, 0x10000
	s_cbranch_scc0 .LNb_done
; __device__ __forceinline__ unsigned cvt_pk_bf16(float lo, float hi) { unsigned r; asm volatile("v_cvt_pk_bf16_f32 %0, %1, %2" : "=v"(r) : "v"(lo), "v"(hi)); return r; }
; __device__ __forceinline__ void phase_norm_mod(const float* x, const float* mod_shift, const float* mod_scale, bf16_t* H, int) {
;     ...
;         for (int r = 0; r < NR; ++r) { const int m = M - 1 - (m0 + r * NGW < M ? m0 + r * NGW : m0); const f32x4* xr = (const f32x4*)(x + (size_t)m * D) + lane;
; #pragma unroll
;             for (int j = 0; j < 4; ++j) v[r][j] = xr[64 * j]; }
; #pragma unroll
;         for (int r = 0; r < NR; ++r) { const int m = M - 1 - (m0 + r * NGW); if (m >= 0) {
;             const int b = m >> 12; float s = 0.f;
; #pragma unroll
;             for (int j = 0; j < 4; ++j) s += (v[r][j].x * v[r][j].x + v[r][j].y * v[r][j].y) + (v[r][j].z * v[r][j].z + v[r][j].w * v[r][j].w);
;             const float rstd = 1.0f / sqrtf(wave_sum(s) * (1.f / D) + 1e-6f);
;             const f32x4* sh = (const f32x4*)(mod_shift + (size_t)b * 6144) + lane;
;             const f32x4* sc = (const f32x4*)(mod_scale + (size_t)b * 6144) + lane;
;             u32x2* o = (u32x2*)(H + (size_t)m * D) + lane;
; #pragma unroll
;             for (int j = 0; j < 4; ++j) { const f32x4 a = sh[64 * j], c = sc[64 * j]; const f32x4 h = v[r][j] * rstd * (c + 1.0f) + a;
;                 u32x2 w; w.x = cvt_pk_bf16(h.x, h.y); w.y = cvt_pk_bf16(h.z, h.w); o[64 * j] = w; } } }
	s_waitcnt vmcnt(24)
	v_pk_mul_f32 v[172:173], v[48:49], v[48:49]
	v_pk_mul_f32 v[174:175], v[50:51], v[50:51]
	v_pk_fma_f32 v[172:173], v[52:53], v[52:53], v[172:173]
	v_pk_fma_f32 v[174:175], v[54:55], v[54:55], v[174:175]
	v_pk_fma_f32 v[172:173], v[56:57], v[56:57], v[172:173]
	v_pk_fma_f32 v[174:175], v[58:59], v[58:59], v[174:175]
	v_pk_fma_f32 v[172:173], v[60:61], v[60:61], v[172:173]
	v_pk_fma_f32 v[174:175], v[62:63], v[62:63], v[174:175]
	v_pk_add_f32 v[172:173], v[172:173], v[174:175]
	s_sub_u32 s3, 0xffff, s19
	s_lshl_b32 s4, s3, 11
	v_add_f32_e32 v160, v172, v173
	s_add_u32 s16, s88, s4
	s_addc_u32 s17, s89, 0
	s_nop 1
	v_add_f32_dpp v160, v160, v160 quad_perm:[1,0,3,2] row_mask:0xf bank_mask:0xf bound_ctrl:1
	s_nop 1
	v_add_f32_dpp v160, v160, v160 quad_perm:[2,3,0,1] row_mask:0xf bank_mask:0xf bound_ctrl:1
	s_nop 1
	v_add_f32_dpp v160, v160, v160 row_half_mirror row_mask:0xf bank_mask:0xf bound_ctrl:1
	s_nop 1
	v_add_f32_dpp v160, v160, v160 row_mirror row_mask:0xf bank_mask:0xf bound_ctrl:1
	s_add_u32 s16, s16, 0x3c00000
	s_addc_u32 s17, s17, 0
	v_readlane_b32 s4, v160, 0
	v_readlane_b32 s5, v160, 16
	v_readlane_b32 s3, v160, 32
	s_nop 1
	v_mov_b32_e32 v161, s4
	v_add_f32_e32 v161, s5, v161
	v_readlane_b32 s4, v160, 48
	v_add_f32_e32 v161, s3, v161
	s_nop 1
	v_add_f32_e32 v160, s4, v161
	v_fmamk_f32 v160, v160, 0x3a800000, v170
	v_mul_f32_e32 v161, 0x4f800000, v160
	v_cmp_gt_f32_e32 vcc, v178, v160
	s_nop 1
	v_cndmask_b32_e32 v162, v160, v161, vcc
	v_sqrt_f32_e32 v164, v162
	s_nop 0
	v_add_u32_e32 v165, -1, v164
	v_add_u32_e32 v166, 1, v164
	v_fma_f32 v167, -v165, v164, v162
	v_fma_f32 v168, -v166, v164, v162
	v_cmp_ge_f32_e64 s[4:5], 0, v167
	s_nop 1
	v_cndmask_b32_e64 v164, v164, v165, s[4:5]
	v_cmp_lt_f32_e64 s[4:5], 0, v168
	s_nop 1
	v_cndmask_b32_e64 v164, v164, v166, s[4:5]
	v_mul_f32_e32 v165, 0x37800000, v164
	v_cndmask_b32_e32 v164, v164, v165, vcc
	v_cmp_class_f32_e32 vcc, v162, v171
	s_nop 1
	v_cndmask_b32_e32 v162, v164, v162, vcc
	v_div_scale_f32 v164, s[4:5], v162, v162, 1.0
	v_rcp_f32_e32 v165, v164
	v_div_scale_f32 v166, vcc, 1.0, v162, 1.0
	v_fma_f32 v167, -v164, v165, 1.0
	v_fmac_f32_e32 v165, v167, v165
	v_mul_f32_e32 v167, v166, v165
	v_fma_f32 v168, -v164, v167, v166
	v_fmac_f32_e32 v167, v168, v165
	v_fma_f32 v164, -v164, v167, v166
	v_div_fmas_f32 v164, v164, v165, v167
	v_div_fixup_f32 v162, v164, v162, 1.0
	v_pk_mul_f32 v[48:49], v[48:49], v[162:163] op_sel_hi:[1,0]
	v_pk_mul_f32 v[50:51], v[50:51], v[162:163] op_sel_hi:[1,0]
	v_pk_add_f32 v[64:65], v[64:65], 1.0 op_sel_hi:[1,0]
	v_pk_add_f32 v[66:67], v[66:67], 1.0 op_sel_hi:[1,0]
	v_pk_fma_f32 v[48:49], v[64:65], v[48:49], v[80:81]
	v_pk_fma_f32 v[50:51], v[66:67], v[50:51], v[82:83]
	v_cvt_pk_bf16_f32 v152, v48, v49
	v_cvt_pk_bf16_f32 v153, v50, v51
	v_pk_mul_f32 v[52:53], v[52:53], v[162:163] op_sel_hi:[1,0]
	v_pk_mul_f32 v[54:55], v[54:55], v[162:163] op_sel_hi:[1,0]
	v_pk_add_f32 v[68:69], v[68:69], 1.0 op_sel_hi:[1,0]
	v_pk_add_f32 v[70:71], v[70:71], 1.0 op_sel_hi:[1,0]
	v_pk_fma_f32 v[52:53], v[68:69], v[52:53], v[84:85]
	v_pk_fma_f32 v[54:55], v[70:71], v[54:55], v[86:87]
	v_cvt_pk_bf16_f32 v154, v52, v53
	v_cvt_pk_bf16_f32 v155, v54, v55
	v_pk_mul_f32 v[56:57], v[56:57], v[162:163] op_sel_hi:[1,0]
	v_pk_mul_f32 v[58:59], v[58:59], v[162:163] op_sel_hi:[1,0]
	v_pk_add_f32 v[72:73], v[72:73], 1.0 op_sel_hi:[1,0]
	v_pk_add_f32 v[74:75], v[74:75], 1.0 op_sel_hi:[1,0]
	v_pk_fma_f32 v[56:57], v[72:73], v[56:57], v[88:89]
	v_pk_fma_f32 v[58:59], v[74:75], v[58:59], v[90:91]
	v_cvt_pk_bf16_f32 v156, v56, v57
	v_cvt_pk_bf16_f32 v157, v58, v59
	v_pk_mul_f32 v[60:61], v[60:61], v[162:163] op_sel_hi:[1,0]
	v_pk_mul_f32 v[62:63], v[62:63], v[162:163] op_sel_hi:[1,0]
	v_pk_add_f32 v[76:77], v[76:77], 1.0 op_sel_hi:[1,0]
	v_pk_add_f32 v[78:79], v[78:79], 1.0 op_sel_hi:[1,0]
	v_pk_fma_f32 v[60:61], v[76:77], v[60:61], v[92:93]
	v_pk_fma_f32 v[62:63], v[78:79], v[62:63], v[94:95]
	v_cvt_pk_bf16_f32 v158, v60, v61
	v_cvt_pk_bf16_f32 v159, v62, v63
	global_store_dwordx2 v177, v[152:153], s[16:17]
	global_store_dwordx2 v177, v[154:155], s[16:17] offset:512
	global_store_dwordx2 v177, v[156:157], s[16:17] offset:1024
	global_store_dwordx2 v177, v[158:159], s[16:17] offset:1536
	s_add_i32 s19, s19, s1
	s_cmp_lt_u32 s19, 0x10000
	s_cselect_b32 s3, s19, s0
	s_sub_u32 s3, 0xffff, s3
	s_lshl_b32 s4, s3, 12
	s_add_u32 s6, s86, s4
	s_addc_u32 s7, s87, 0
	s_lshr_b32 s4, s3, 12
	s_mul_i32 s4, s4, 0x6000
	s_add_u32 s12, s88, s4
	s_addc_u32 s13, s89, 0
	s_add_u32 s14, s12, 0x164000
	s_addc_u32 s15, s13, 0
	s_add_u32 s12, s12, 0x163000
	s_addc_u32 s13, s13, 0
	global_load_dwordx4 v[48:51], v176, s[6:7]
	global_load_dwordx4 v[52:55], v176, s[6:7] offset:1024
	global_load_dwordx4 v[56:59], v176, s[6:7] offset:2048
	global_load_dwordx4 v[60:63], v176, s[6:7] offset:3072
	global_load_dwordx4 v[64:67], v176, s[14:15]
	global_load_dwordx4 v[68:71], v176, s[14:15] offset:1024
	global_load_dwordx4 v[72:75], v176, s[14:15] offset:2048
	global_load_dwordx4 v[76:79], v176, s[14:15] offset:3072
	global_load_dwordx4 v[80:83], v176, s[12:13]
	global_load_dwordx4 v[84:87], v176, s[12:13] offset:1024
	global_load_dwordx4 v[88:91], v176, s[12:13] offset:2048
	global_load_dwordx4 v[92:95], v176, s[12:13] offset:3072
	s_cmp_lt_u32 s20, 0x10000
	s_cbranch_scc0 .LNb_done
; __device__ __forceinline__ unsigned cvt_pk_bf16(float lo, float hi) { unsigned r; asm volatile("v_cvt_pk_bf16_f32 %0, %1, %2" : "=v"(r) : "v"(lo), "v"(hi)); return r; }
; __device__ __forceinline__ void phase_norm_mod(const float* x, const float* mod_shift, const float* mod_scale, bf16_t* H, int) {
;     ...
;         for (int r = 0; r < NR; ++r) { const int m = M - 1 - (m0 + r * NGW < M ? m0 + r * NGW : m0); const f32x4* xr = (const f32x4*)(x + (size_t)m * D) + lane;
; #pragma unroll
;             for (int j = 0; j < 4; ++j) v[r][j] = xr[64 * j]; }
; #pragma unroll
;         for (int r = 0; r < NR; ++r) { const int m = M - 1 - (m0 + r * NGW); if (m >= 0) {
;             const int b = m >> 12; float s = 0.f;
; #pragma unroll
;             for (int j = 0; j < 4; ++j) s += (v[r][j].x * v[r][j].x + v[r][j].y * v[r][j].y) + (v[r][j].z * v[r][j].z + v[r][j].w * v[r][j].w);
;             const float rstd = 1.0f / sqrtf(wave_sum(s) * (1.f / D) + 1e-6f);
;             const f32x4* sh = (const f32x4*)(mod_shift + (size_t)b * 6144) + lane;
;             const f32x4* sc = (const f32x4*)(mod_scale + (size_t)b * 6144) + lane;
;             u32x2* o = (u32x2*)(H + (size_t)m * D) + lane;
; #pragma unroll
;             for (int j = 0; j < 4; ++j) { const f32x4 a = sh[64 * j], c = sc[64 * j]; const f32x4 h = v[r][j] * rstd * (c + 1.0f) + a;
;                 u32x2 w; w.x = cvt_pk_bf16(h.x, h.y); w.y = cvt_pk_bf16(h.z, h.w); o[64 * j] = w; } } }
	s_waitcnt vmcnt(24)
	v_pk_mul_f32 v[172:173], v[96:97], v[96:97]
	v_pk_mul_f32 v[174:175], v[98:99], v[98:99]
	v_pk_fma_f32 v[172:173], v[100:101], v[100:101], v[172:173]
	v_pk_fma_f32 v[174:175], v[102:103], v[102:103], v[174:175]
	v_pk_fma_f32 v[172:173], v[104:105], v[104:105], v[172:173]
	v_pk_fma_f32 v[174:175], v[106:107], v[106:107], v[174:175]
	v_pk_fma_f32 v[172:173], v[108:109], v[108:109], v[172:173]
	v_pk_fma_f32 v[174:175], v[110:111], v[110:111], v[174:175]
	v_pk_add_f32 v[172:173], v[172:173], v[174:175]
	s_sub_u32 s3, 0xffff, s20
	s_lshl_b32 s4, s3, 11
	v_add_f32_e32 v160, v172, v173
	s_add_u32 s16, s88, s4
	s_addc_u32 s17, s89, 0
	s_nop 1
	v_add_f32_dpp v160, v160, v160 quad_perm:[1,0,3,2] row_mask:0xf bank_mask:0xf bound_ctrl:1
	s_nop 1
	v_add_f32_dpp v160, v160, v160 quad_perm:[2,3,0,1] row_mask:0xf bank_mask:0xf bound_ctrl:1
	s_nop 1
	v_add_f32_dpp v160, v160, v160 row_half_mirror row_mask:0xf bank_mask:0xf bound_ctrl:1
	s_nop 1
	v_add_f32_dpp v160, v160, v160 row_mirror row_mask:0xf bank_mask:0xf bound_ctrl:1
	s_add_u32 s16, s16, 0x3c00000
	s_addc_u32 s17, s17, 0
	v_readlane_b32 s4, v160, 0
	v_readlane_b32 s5, v160, 16
	v_readlane_b32 s3, v160, 32
	s_nop 1
	v_mov_b32_e32 v161, s4
	v_add_f32_e32 v161, s5, v161
	v_readlane_b32 s4, v160, 48
	v_add_f32_e32 v161, s3, v161
	s_nop 1
	v_add_f32_e32 v160, s4, v161
	v_fmamk_f32 v160, v160, 0x3a800000, v170
	v_mul_f32_e32 v161, 0x4f800000, v160
	v_cmp_gt_f32_e32 vcc, v178, v160
	s_nop 1
	v_cndmask_b32_e32 v162, v160, v161, vcc
	v_sqrt_f32_e32 v164, v162
	s_nop 0
	v_add_u32_e32 v165, -1, v164
	v_add_u32_e32 v166, 1, v164
	v_fma_f32 v167, -v165, v164, v162
	v_fma_f32 v168, -v166, v164, v162
	v_cmp_ge_f32_e64 s[4:5], 0, v167
	s_nop 1
	v_cndmask_b32_e64 v164, v164, v165, s[4:5]
	v_cmp_lt_f32_e64 s[4:5], 0, v168
	s_nop 1
	v_cndmask_b32_e64 v164, v164, v166, s[4:5]
	v_mul_f32_e32 v165, 0x37800000, v164
	v_cndmask_b32_e32 v164, v164, v165, vcc
	v_cmp_class_f32_e32 vcc, v162, v171
	s_nop 1
	v_cndmask_b32_e32 v162, v164, v162, vcc
	v_div_scale_f32 v164, s[4:5], v162, v162, 1.0
	v_rcp_f32_e32 v165, v164
	v_div_scale_f32 v166, vcc, 1.0, v162, 1.0
	v_fma_f32 v167, -v164, v165, 1.0
	v_fmac_f32_e32 v165, v167, v165
	v_mul_f32_e32 v167, v166, v165
	v_fma_f32 v168, -v164, v167, v166
	v_fmac_f32_e32 v167, v168, v165
	v_fma_f32 v164, -v164, v167, v166
	v_div_fmas_f32 v164, v164, v165, v167
	v_div_fixup_f32 v162, v164, v162, 1.0
	v_pk_mul_f32 v[96:97], v[96:97], v[162:163] op_sel_hi:[1,0]
	v_pk_mul_f32 v[98:99], v[98:99], v[162:163] op_sel_hi:[1,0]
	v_pk_add_f32 v[112:113], v[112:113], 1.0 op_sel_hi:[1,0]
	v_pk_add_f32 v[114:115], v[114:115], 1.0 op_sel_hi:[1,0]
	v_pk_fma_f32 v[96:97], v[112:113], v[96:97], v[128:129]
	v_pk_fma_f32 v[98:99], v[114:115], v[98:99], v[130:131]
	v_cvt_pk_bf16_f32 v152, v96, v97
	v_cvt_pk_bf16_f32 v153, v98, v99
	v_pk_mul_f32 v[100:101], v[100:101], v[162:163] op_sel_hi:[1,0]
	v_pk_mul_f32 v[102:103], v[102:103], v[162:163] op_sel_hi:[1,0]
	v_pk_add_f32 v[116:117], v[116:117], 1.0 op_sel_hi:[1,0]
	v_pk_add_f32 v[118:119], v[118:119], 1.0 op_sel_hi:[1,0]
	v_pk_fma_f32 v[100:101], v[116:117], v[100:101], v[132:133]
	v_pk_fma_f32 v[102:103], v[118:119], v[102:103], v[134:135]
	v_cvt_pk_bf16_f32 v154, v100, v101
	v_cvt_pk_bf16_f32 v155, v102, v103
	v_pk_mul_f32 v[104:105], v[104:105], v[162:163] op_sel_hi:[1,0]
	v_pk_mul_f32 v[106:107], v[106:107], v[162:163] op_sel_hi:[1,0]
	v_pk_add_f32 v[120:121], v[120:121], 1.0 op_sel_hi:[1,0]
	v_pk_add_f32 v[122:123], v[122:123], 1.0 op_sel_hi:[1,0]
	v_pk_fma_f32 v[104:105], v[120:121], v[104:105], v[136:137]
	v_pk_fma_f32 v[106:107], v[122:123], v[106:107], v[138:139]
	v_cvt_pk_bf16_f32 v156, v104, v105
	v_cvt_pk_bf16_f32 v157, v106, v107
	v_pk_mul_f32 v[108:109], v[108:109], v[162:163] op_sel_hi:[1,0]
	v_pk_mul_f32 v[110:111], v[110:111], v[162:163] op_sel_hi:[1,0]
	v_pk_add_f32 v[124:125], v[124:125], 1.0 op_sel_hi:[1,0]
	v_pk_add_f32 v[126:127], v[126:127], 1.0 op_sel_hi:[1,0]
	v_pk_fma_f32 v[108:109], v[124:125], v[108:109], v[140:141]
	v_pk_fma_f32 v[110:111], v[126:127], v[110:111], v[142:143]
	v_cvt_pk_bf16_f32 v158, v108, v109
	v_cvt_pk_bf16_f32 v159, v110, v111
	global_store_dwordx2 v177, v[152:153], s[16:17]
	global_store_dwordx2 v177, v[154:155], s[16:17] offset:512
	global_store_dwordx2 v177, v[156:157], s[16:17] offset:1024
	global_store_dwordx2 v177, v[158:159], s[16:17] offset:1536
	s_add_i32 s20, s20, s1
	s_cmp_lt_u32 s20, 0x10000
	s_cselect_b32 s3, s20, s0
	s_sub_u32 s3, 0xffff, s3
	s_lshl_b32 s4, s3, 12
	s_add_u32 s6, s86, s4
	s_addc_u32 s7, s87, 0
	s_lshr_b32 s4, s3, 12
	s_mul_i32 s4, s4, 0x6000
	s_add_u32 s12, s88, s4
	s_addc_u32 s13, s89, 0
	s_add_u32 s14, s12, 0x164000
	s_addc_u32 s15, s13, 0
	s_add_u32 s12, s12, 0x163000
	s_addc_u32 s13, s13, 0
	global_load_dwordx4 v[96:99], v176, s[6:7]
	global_load_dwordx4 v[100:103], v176, s[6:7] offset:1024
	global_load_dwordx4 v[104:107], v176, s[6:7] offset:2048
	global_load_dwordx4 v[108:111], v176, s[6:7] offset:3072
	global_load_dwordx4 v[112:115], v176, s[14:15]
	global_load_dwordx4 v[116:119], v176, s[14:15] offset:1024
	global_load_dwordx4 v[120:123], v176, s[14:15] offset:2048
	global_load_dwordx4 v[124:127], v176, s[14:15] offset:3072
	global_load_dwordx4 v[128:131], v176, s[12:13]
	global_load_dwordx4 v[132:135], v176, s[12:13] offset:1024
	global_load_dwordx4 v[136:139], v176, s[12:13] offset:2048
	global_load_dwordx4 v[140:143], v176, s[12:13] offset:3072
	s_branch .LNb_loop
.LNb_done:
	s_waitcnt vmcnt(0)
.LBB0_2213:
	s_or_b64 exec, exec, s[10:11]
